# EpiRes epilogue: hoist all 32 residual loads, counted vmcnt, batched bpermute
# speedup vs baseline: 1.0042x; 1.0042x over previous
; __device__ __forceinline__ unsigned cvt_pk_bf16(float lo, float hi) { unsigned r; asm volatile("v_cvt_pk_bf16_f32 %0, %1, %2" : "=v"(r) : "v"(lo), "v"(hi)); return r; }
;     __device__ __forceinline__ void operator()(const f32x4 (&acc)[2][2][4][2], const Unit& u, int wr, int wc, int fr, int fq) const {
;     ...
;         const int row0 = u.pm * BM + wr * 64 + fr; const int col0 = u.pn * BM + wc * 32 + 4 * fq;
; #pragma unroll
;         for (int ai = 0; ai < 2; ++ai)
; #pragma unroll
;             for (int m = 0; m < 4; ++m) { const size_t off = (size_t)(row0 + ai * HALF + m * 16) * ldc + col0; float q = 0.f;
;                 u32x2_ bv[2][2];
; #pragma unroll
;                 for (int bj = 0; bj < 2; ++bj)
; #pragma unroll
;                     for (int n = 0; n < 2; ++n) bv[bj][n] = *(const u32x2_*)(base + off + bj * HALF + n * 16);
; #pragma unroll
;                 for (int bj = 0; bj < 2; ++bj)
; #pragma unroll
;                     for (int n = 0; n < 2; ++n) { const u32x2_ bb = bv[bj][n]; f32x4 v = acc[ai][bj][m][n];
;                         v[0] += __uint_as_float(bb.x << 16); v[1] += __uint_as_float(bb.x & 0xffff0000u); v[2] += __uint_as_float(bb.y << 16); v[3] += __uint_as_float(bb.y & 0xffff0000u);
;                         u32x2_ w; w.x = cvt_pk_bf16(v[0], v[1]); w.y = cvt_pk_bf16(v[2], v[3]);
;                         *(u32x2_*)(xb + off + bj * HALF + n * 16) = w;
;                         q += (v[0] * v[0] + v[1] * v[1]) + (v[2] * v[2] + v[3] * v[3]); }
;                 q += __shfl_xor(q, 16); q += __shfl_xor(q, 32);
;                 if (fq == 0) red[wc * 256 + ai * HALF + wr * 64 + m * 16 + fr] = q; }
.LBB0_316:
	s_lshl_b32 s20, s20, 8
	v_add_u32_e32 v218, s20, v140
	v_lshl_or_b32 v220, s0, 8, v142
	v_ashrrev_i32_e32 v219, 31, v218
	v_ashrrev_i32_e32 v221, 31, v220
	v_lshlrev_b64 v[216:217], 11, v[218:219]
	v_lshl_add_u64 v[216:217], v[216:217], 0, v[220:221]
	v_lshlrev_b64 v[216:217], 1, v[216:217]
	v_lshl_add_u64 v[218:219], s[8:9], 0, v[216:217]
	v_lshl_add_u64 v[216:217], s[6:7], 0, v[216:217]
	s_movk_i32 s60, 0x1c00
	s_mov_b64 s[22:23], 0x10000
	s_mov_b64 s[24:25], 0x50000
	v_xor_b32_e32 v222, 16, v236
	v_xor_b32_e32 v223, 32, v236
	global_load_dwordx2 v[146:147], v[216:217], off
	global_load_dwordx2 v[148:149], v[216:217], off offset:32
	global_load_dwordx2 v[150:151], v[216:217], off offset:256
	global_load_dwordx2 v[152:153], v[216:217], off offset:288
	v_lshl_add_u64 v[216:217], v[216:217], 0, s[22:23]
	global_load_dwordx2 v[154:155], v[216:217], off
	global_load_dwordx2 v[156:157], v[216:217], off offset:32
	global_load_dwordx2 v[158:159], v[216:217], off offset:256
	global_load_dwordx2 v[160:161], v[216:217], off offset:288
	v_lshl_add_u64 v[216:217], v[216:217], 0, s[22:23]
	global_load_dwordx2 v[162:163], v[216:217], off
	global_load_dwordx2 v[164:165], v[216:217], off offset:32
	global_load_dwordx2 v[166:167], v[216:217], off offset:256
	global_load_dwordx2 v[168:169], v[216:217], off offset:288
	v_lshl_add_u64 v[216:217], v[216:217], 0, s[22:23]
	global_load_dwordx2 v[170:171], v[216:217], off
	global_load_dwordx2 v[172:173], v[216:217], off offset:32
	global_load_dwordx2 v[174:175], v[216:217], off offset:256
	global_load_dwordx2 v[176:177], v[216:217], off offset:288
	v_lshl_add_u64 v[216:217], v[216:217], 0, s[24:25]
	global_load_dwordx2 v[178:179], v[216:217], off
	global_load_dwordx2 v[180:181], v[216:217], off offset:32
	global_load_dwordx2 v[182:183], v[216:217], off offset:256
	global_load_dwordx2 v[184:185], v[216:217], off offset:288
	v_lshl_add_u64 v[216:217], v[216:217], 0, s[22:23]
	global_load_dwordx2 v[186:187], v[216:217], off
	global_load_dwordx2 v[188:189], v[216:217], off offset:32
	global_load_dwordx2 v[190:191], v[216:217], off offset:256
	global_load_dwordx2 v[192:193], v[216:217], off offset:288
	v_lshl_add_u64 v[216:217], v[216:217], 0, s[22:23]
	global_load_dwordx2 v[194:195], v[216:217], off
	global_load_dwordx2 v[196:197], v[216:217], off offset:32
	global_load_dwordx2 v[198:199], v[216:217], off offset:256
	global_load_dwordx2 v[200:201], v[216:217], off offset:288
	v_lshl_add_u64 v[216:217], v[216:217], 0, s[22:23]
	global_load_dwordx2 v[204:205], v[216:217], off
	global_load_dwordx2 v[206:207], v[216:217], off offset:32
	global_load_dwordx2 v[136:137], v[216:217], off offset:256
	global_load_dwordx2 v[138:139], v[216:217], off offset:288
	v_lshlrev_b32_e32 v222, 2, v222
	v_lshlrev_b32_e32 v223, 2, v223
	s_waitcnt vmcnt(31)
	v_lshlrev_b32_e32 v220, 16, v146
	v_and_b32_e32 v146, 0xffff0000, v146
	v_lshlrev_b32_e32 v221, 16, v147
	v_and_b32_e32 v147, 0xffff0000, v147
	v_add_f32_e32 v126, v126, v220
	v_add_f32_e32 v127, v127, v146
	v_add_f32_e32 v128, v128, v221
	v_add_f32_e32 v129, v129, v147
	v_cvt_pk_bf16_f32 v146, v126, v127
	v_cvt_pk_bf16_f32 v147, v128, v129
	global_store_dwordx2 v[218:219], v[146:147], off
	v_mul_f32_e32 v220, v127, v127
	v_mul_f32_e32 v221, v129, v129
	v_fmac_f32_e32 v220, v126, v126
	v_fmac_f32_e32 v221, v128, v128
	v_add_f32_e32 v126, v220, v221
	s_waitcnt vmcnt(31)
	v_lshlrev_b32_e32 v220, 16, v148
	v_and_b32_e32 v148, 0xffff0000, v148
	v_lshlrev_b32_e32 v221, 16, v149
	v_and_b32_e32 v149, 0xffff0000, v149
	v_add_f32_e32 v122, v122, v220
	v_add_f32_e32 v123, v123, v148
	v_add_f32_e32 v124, v124, v221
	v_add_f32_e32 v125, v125, v149
	v_cvt_pk_bf16_f32 v148, v122, v123
	v_cvt_pk_bf16_f32 v149, v124, v125
	global_store_dwordx2 v[218:219], v[148:149], off offset:32
	v_mul_f32_e32 v220, v123, v123
	v_mul_f32_e32 v221, v125, v125
	v_fmac_f32_e32 v220, v122, v122
	v_fmac_f32_e32 v221, v124, v124
	v_add_f32_e32 v122, v220, v221
	s_waitcnt vmcnt(31)
	v_lshlrev_b32_e32 v220, 16, v150
	v_and_b32_e32 v150, 0xffff0000, v150
	v_lshlrev_b32_e32 v221, 16, v151
	v_and_b32_e32 v151, 0xffff0000, v151
	v_add_f32_e32 v118, v118, v220
	v_add_f32_e32 v119, v119, v150
	v_add_f32_e32 v120, v120, v221
	v_add_f32_e32 v121, v121, v151
	v_cvt_pk_bf16_f32 v150, v118, v119
	v_cvt_pk_bf16_f32 v151, v120, v121
	global_store_dwordx2 v[218:219], v[150:151], off offset:256
	v_mul_f32_e32 v220, v119, v119
	v_mul_f32_e32 v221, v121, v121
	v_fmac_f32_e32 v220, v118, v118
	v_fmac_f32_e32 v221, v120, v120
	v_add_f32_e32 v118, v220, v221
	s_waitcnt vmcnt(31)
	v_lshlrev_b32_e32 v220, 16, v152
	v_and_b32_e32 v152, 0xffff0000, v152
	v_lshlrev_b32_e32 v221, 16, v153
	v_and_b32_e32 v153, 0xffff0000, v153
	v_add_f32_e32 v114, v114, v220
	v_add_f32_e32 v115, v115, v152
	v_add_f32_e32 v116, v116, v221
	v_add_f32_e32 v117, v117, v153
	v_cvt_pk_bf16_f32 v152, v114, v115
	v_cvt_pk_bf16_f32 v153, v116, v117
	global_store_dwordx2 v[218:219], v[152:153], off offset:288
	v_mul_f32_e32 v220, v115, v115
	v_mul_f32_e32 v221, v117, v117
	v_fmac_f32_e32 v220, v114, v114
	v_fmac_f32_e32 v221, v116, v116
	v_add_f32_e32 v114, v220, v221
	v_add_f32_e32 v122, v126, v122
	v_add_f32_e32 v118, v122, v118
	v_add_f32_e32 v114, v118, v114
	v_lshl_add_u64 v[218:219], v[218:219], 0, s[22:23]
	s_waitcnt vmcnt(31)
	v_lshlrev_b32_e32 v220, 16, v154
	v_and_b32_e32 v154, 0xffff0000, v154
	v_lshlrev_b32_e32 v221, 16, v155
	v_and_b32_e32 v155, 0xffff0000, v155
	v_add_f32_e32 v110, v110, v220
	v_add_f32_e32 v111, v111, v154
	v_add_f32_e32 v112, v112, v221
	v_add_f32_e32 v113, v113, v155
	v_cvt_pk_bf16_f32 v154, v110, v111
	v_cvt_pk_bf16_f32 v155, v112, v113
	global_store_dwordx2 v[218:219], v[154:155], off
	v_mul_f32_e32 v220, v111, v111
	v_mul_f32_e32 v221, v113, v113
	v_fmac_f32_e32 v220, v110, v110
	v_fmac_f32_e32 v221, v112, v112
	v_add_f32_e32 v110, v220, v221
	s_waitcnt vmcnt(31)
; __device__ __forceinline__ unsigned cvt_pk_bf16(float lo, float hi) { unsigned r; asm volatile("v_cvt_pk_bf16_f32 %0, %1, %2" : "=v"(r) : "v"(lo), "v"(hi)); return r; }
;     __device__ __forceinline__ void operator()(const f32x4 (&acc)[2][2][4][2], const Unit& u, int wr, int wc, int fr, int fq) const {
;     ...
;                     for (int n = 0; n < 2; ++n) bv[bj][n] = *(const u32x2_*)(base + off + bj * HALF + n * 16);
; #pragma unroll
;                 for (int bj = 0; bj < 2; ++bj)
; #pragma unroll
;                     for (int n = 0; n < 2; ++n) { const u32x2_ bb = bv[bj][n]; f32x4 v = acc[ai][bj][m][n];
;                         v[0] += __uint_as_float(bb.x << 16); v[1] += __uint_as_float(bb.x & 0xffff0000u); v[2] += __uint_as_float(bb.y << 16); v[3] += __uint_as_float(bb.y & 0xffff0000u);
;                         u32x2_ w; w.x = cvt_pk_bf16(v[0], v[1]); w.y = cvt_pk_bf16(v[2], v[3]);
;                         *(u32x2_*)(xb + off + bj * HALF + n * 16) = w;
;                         q += (v[0] * v[0] + v[1] * v[1]) + (v[2] * v[2] + v[3] * v[3]); }
	v_lshlrev_b32_e32 v220, 16, v156
	v_and_b32_e32 v156, 0xffff0000, v156
	v_lshlrev_b32_e32 v221, 16, v157
	v_and_b32_e32 v157, 0xffff0000, v157
	v_add_f32_e32 v106, v106, v220
	v_add_f32_e32 v107, v107, v156
	v_add_f32_e32 v108, v108, v221
	v_add_f32_e32 v109, v109, v157
	v_cvt_pk_bf16_f32 v156, v106, v107
	v_cvt_pk_bf16_f32 v157, v108, v109
	global_store_dwordx2 v[218:219], v[156:157], off offset:32
	v_mul_f32_e32 v220, v107, v107
	v_mul_f32_e32 v221, v109, v109
	v_fmac_f32_e32 v220, v106, v106
	v_fmac_f32_e32 v221, v108, v108
	v_add_f32_e32 v106, v220, v221
	s_waitcnt vmcnt(31)
	v_lshlrev_b32_e32 v220, 16, v158
	v_and_b32_e32 v158, 0xffff0000, v158
	v_lshlrev_b32_e32 v221, 16, v159
	v_and_b32_e32 v159, 0xffff0000, v159
	v_add_f32_e32 v102, v102, v220
	v_add_f32_e32 v103, v103, v158
	v_add_f32_e32 v104, v104, v221
	v_add_f32_e32 v105, v105, v159
	v_cvt_pk_bf16_f32 v158, v102, v103
	v_cvt_pk_bf16_f32 v159, v104, v105
	global_store_dwordx2 v[218:219], v[158:159], off offset:256
	v_mul_f32_e32 v220, v103, v103
	v_mul_f32_e32 v221, v105, v105
	v_fmac_f32_e32 v220, v102, v102
	v_fmac_f32_e32 v221, v104, v104
	v_add_f32_e32 v102, v220, v221
	s_waitcnt vmcnt(31)
	v_lshlrev_b32_e32 v220, 16, v160
	v_and_b32_e32 v160, 0xffff0000, v160
	v_lshlrev_b32_e32 v221, 16, v161
	v_and_b32_e32 v161, 0xffff0000, v161
	v_add_f32_e32 v98, v98, v220
	v_add_f32_e32 v99, v99, v160
	v_add_f32_e32 v100, v100, v221
	v_add_f32_e32 v101, v101, v161
	v_cvt_pk_bf16_f32 v160, v98, v99
	v_cvt_pk_bf16_f32 v161, v100, v101
	global_store_dwordx2 v[218:219], v[160:161], off offset:288
	v_mul_f32_e32 v220, v99, v99
	v_mul_f32_e32 v221, v101, v101
	v_fmac_f32_e32 v220, v98, v98
	v_fmac_f32_e32 v221, v100, v100
	v_add_f32_e32 v98, v220, v221
	v_add_f32_e32 v106, v110, v106
	v_add_f32_e32 v102, v106, v102
	v_add_f32_e32 v98, v102, v98
	v_lshl_add_u64 v[218:219], v[218:219], 0, s[22:23]
	s_waitcnt vmcnt(31)
	v_lshlrev_b32_e32 v220, 16, v162
	v_and_b32_e32 v162, 0xffff0000, v162
	v_lshlrev_b32_e32 v221, 16, v163
	v_and_b32_e32 v163, 0xffff0000, v163
	v_add_f32_e32 v94, v94, v220
	v_add_f32_e32 v95, v95, v162
	v_add_f32_e32 v96, v96, v221
	v_add_f32_e32 v97, v97, v163
	v_cvt_pk_bf16_f32 v162, v94, v95
	v_cvt_pk_bf16_f32 v163, v96, v97
	global_store_dwordx2 v[218:219], v[162:163], off
	v_mul_f32_e32 v220, v95, v95
	v_mul_f32_e32 v221, v97, v97
	v_fmac_f32_e32 v220, v94, v94
	v_fmac_f32_e32 v221, v96, v96
	v_add_f32_e32 v94, v220, v221
	s_waitcnt vmcnt(31)
	v_lshlrev_b32_e32 v220, 16, v164
	v_and_b32_e32 v164, 0xffff0000, v164
	v_lshlrev_b32_e32 v221, 16, v165
	v_and_b32_e32 v165, 0xffff0000, v165
	v_add_f32_e32 v90, v90, v220
	v_add_f32_e32 v91, v91, v164
	v_add_f32_e32 v92, v92, v221
	v_add_f32_e32 v93, v93, v165
	v_cvt_pk_bf16_f32 v164, v90, v91
	v_cvt_pk_bf16_f32 v165, v92, v93
	global_store_dwordx2 v[218:219], v[164:165], off offset:32
	v_mul_f32_e32 v220, v91, v91
	v_mul_f32_e32 v221, v93, v93
	v_fmac_f32_e32 v220, v90, v90
	v_fmac_f32_e32 v221, v92, v92
	v_add_f32_e32 v90, v220, v221
	s_waitcnt vmcnt(31)
	v_lshlrev_b32_e32 v220, 16, v166
	v_and_b32_e32 v166, 0xffff0000, v166
	v_lshlrev_b32_e32 v221, 16, v167
	v_and_b32_e32 v167, 0xffff0000, v167
	v_add_f32_e32 v86, v86, v220
	v_add_f32_e32 v87, v87, v166
	v_add_f32_e32 v88, v88, v221
	v_add_f32_e32 v89, v89, v167
	v_cvt_pk_bf16_f32 v166, v86, v87
	v_cvt_pk_bf16_f32 v167, v88, v89
	global_store_dwordx2 v[218:219], v[166:167], off offset:256
	v_mul_f32_e32 v220, v87, v87
	v_mul_f32_e32 v221, v89, v89
	v_fmac_f32_e32 v220, v86, v86
	v_fmac_f32_e32 v221, v88, v88
	v_add_f32_e32 v86, v220, v221
	s_waitcnt vmcnt(31)
	v_lshlrev_b32_e32 v220, 16, v168
	v_and_b32_e32 v168, 0xffff0000, v168
	v_lshlrev_b32_e32 v221, 16, v169
	v_and_b32_e32 v169, 0xffff0000, v169
	v_add_f32_e32 v82, v82, v220
	v_add_f32_e32 v83, v83, v168
	v_add_f32_e32 v84, v84, v221
	v_add_f32_e32 v85, v85, v169
	v_cvt_pk_bf16_f32 v168, v82, v83
	v_cvt_pk_bf16_f32 v169, v84, v85
	global_store_dwordx2 v[218:219], v[168:169], off offset:288
	v_mul_f32_e32 v220, v83, v83
	v_mul_f32_e32 v221, v85, v85
	v_fmac_f32_e32 v220, v82, v82
	v_fmac_f32_e32 v221, v84, v84
	v_add_f32_e32 v82, v220, v221
	v_add_f32_e32 v90, v94, v90
	v_add_f32_e32 v86, v90, v86
	v_add_f32_e32 v82, v86, v82
	v_lshl_add_u64 v[218:219], v[218:219], 0, s[22:23]
	s_waitcnt vmcnt(31)
	v_lshlrev_b32_e32 v220, 16, v170
	v_and_b32_e32 v170, 0xffff0000, v170
	v_lshlrev_b32_e32 v221, 16, v171
	v_and_b32_e32 v171, 0xffff0000, v171
	v_add_f32_e32 v78, v78, v220
	v_add_f32_e32 v79, v79, v170
	v_add_f32_e32 v80, v80, v221
	v_add_f32_e32 v81, v81, v171
	v_cvt_pk_bf16_f32 v170, v78, v79
	v_cvt_pk_bf16_f32 v171, v80, v81
	global_store_dwordx2 v[218:219], v[170:171], off
	v_mul_f32_e32 v220, v79, v79
	v_mul_f32_e32 v221, v81, v81
	v_fmac_f32_e32 v220, v78, v78
	v_fmac_f32_e32 v221, v80, v80
	v_add_f32_e32 v78, v220, v221
	s_waitcnt vmcnt(31)
	v_lshlrev_b32_e32 v220, 16, v172
	v_and_b32_e32 v172, 0xffff0000, v172
	v_lshlrev_b32_e32 v221, 16, v173
	v_and_b32_e32 v173, 0xffff0000, v173
	v_add_f32_e32 v74, v74, v220
	v_add_f32_e32 v75, v75, v172
	v_add_f32_e32 v76, v76, v221
	v_add_f32_e32 v77, v77, v173
	v_cvt_pk_bf16_f32 v172, v74, v75
	v_cvt_pk_bf16_f32 v173, v76, v77
	global_store_dwordx2 v[218:219], v[172:173], off offset:32
	v_mul_f32_e32 v220, v75, v75
	v_mul_f32_e32 v221, v77, v77
	v_fmac_f32_e32 v220, v74, v74
	v_fmac_f32_e32 v221, v76, v76
	v_add_f32_e32 v74, v220, v221
	s_waitcnt vmcnt(31)
; __device__ __forceinline__ unsigned cvt_pk_bf16(float lo, float hi) { unsigned r; asm volatile("v_cvt_pk_bf16_f32 %0, %1, %2" : "=v"(r) : "v"(lo), "v"(hi)); return r; }
;     __device__ __forceinline__ void operator()(const f32x4 (&acc)[2][2][4][2], const Unit& u, int wr, int wc, int fr, int fq) const {
;     ...
;                     for (int n = 0; n < 2; ++n) bv[bj][n] = *(const u32x2_*)(base + off + bj * HALF + n * 16);
; #pragma unroll
;                 for (int bj = 0; bj < 2; ++bj)
; #pragma unroll
;                     for (int n = 0; n < 2; ++n) { const u32x2_ bb = bv[bj][n]; f32x4 v = acc[ai][bj][m][n];
;                         v[0] += __uint_as_float(bb.x << 16); v[1] += __uint_as_float(bb.x & 0xffff0000u); v[2] += __uint_as_float(bb.y << 16); v[3] += __uint_as_float(bb.y & 0xffff0000u);
;                         u32x2_ w; w.x = cvt_pk_bf16(v[0], v[1]); w.y = cvt_pk_bf16(v[2], v[3]);
;                         *(u32x2_*)(xb + off + bj * HALF + n * 16) = w;
;                         q += (v[0] * v[0] + v[1] * v[1]) + (v[2] * v[2] + v[3] * v[3]); }
	v_lshlrev_b32_e32 v220, 16, v174
	v_and_b32_e32 v174, 0xffff0000, v174
	v_lshlrev_b32_e32 v221, 16, v175
	v_and_b32_e32 v175, 0xffff0000, v175
	v_add_f32_e32 v70, v70, v220
	v_add_f32_e32 v71, v71, v174
	v_add_f32_e32 v72, v72, v221
	v_add_f32_e32 v73, v73, v175
	v_cvt_pk_bf16_f32 v174, v70, v71
	v_cvt_pk_bf16_f32 v175, v72, v73
	global_store_dwordx2 v[218:219], v[174:175], off offset:256
	v_mul_f32_e32 v220, v71, v71
	v_mul_f32_e32 v221, v73, v73
	v_fmac_f32_e32 v220, v70, v70
	v_fmac_f32_e32 v221, v72, v72
	v_add_f32_e32 v70, v220, v221
	s_waitcnt vmcnt(31)
	v_lshlrev_b32_e32 v220, 16, v176
	v_and_b32_e32 v176, 0xffff0000, v176
	v_lshlrev_b32_e32 v221, 16, v177
	v_and_b32_e32 v177, 0xffff0000, v177
	v_add_f32_e32 v66, v66, v220
	v_add_f32_e32 v67, v67, v176
	v_add_f32_e32 v68, v68, v221
	v_add_f32_e32 v69, v69, v177
	v_cvt_pk_bf16_f32 v176, v66, v67
	v_cvt_pk_bf16_f32 v177, v68, v69
	global_store_dwordx2 v[218:219], v[176:177], off offset:288
	v_mul_f32_e32 v220, v67, v67
	v_mul_f32_e32 v221, v69, v69
	v_fmac_f32_e32 v220, v66, v66
	v_fmac_f32_e32 v221, v68, v68
	v_add_f32_e32 v66, v220, v221
	v_add_f32_e32 v74, v78, v74
	v_add_f32_e32 v70, v74, v70
	v_add_f32_e32 v66, v70, v66
	v_lshl_add_u64 v[218:219], v[218:219], 0, s[24:25]
	s_waitcnt vmcnt(31)
	v_lshlrev_b32_e32 v220, 16, v178
	v_and_b32_e32 v178, 0xffff0000, v178
	v_lshlrev_b32_e32 v221, 16, v179
	v_and_b32_e32 v179, 0xffff0000, v179
	v_add_f32_e32 v62, v62, v220
	v_add_f32_e32 v63, v63, v178
	v_add_f32_e32 v64, v64, v221
	v_add_f32_e32 v65, v65, v179
	v_cvt_pk_bf16_f32 v178, v62, v63
	v_cvt_pk_bf16_f32 v179, v64, v65
	global_store_dwordx2 v[218:219], v[178:179], off
	v_mul_f32_e32 v220, v63, v63
	v_mul_f32_e32 v221, v65, v65
	v_fmac_f32_e32 v220, v62, v62
	v_fmac_f32_e32 v221, v64, v64
	v_add_f32_e32 v62, v220, v221
	s_waitcnt vmcnt(31)
	v_lshlrev_b32_e32 v220, 16, v180
	v_and_b32_e32 v180, 0xffff0000, v180
	v_lshlrev_b32_e32 v221, 16, v181
	v_and_b32_e32 v181, 0xffff0000, v181
	v_add_f32_e32 v58, v58, v220
	v_add_f32_e32 v59, v59, v180
	v_add_f32_e32 v60, v60, v221
	v_add_f32_e32 v61, v61, v181
	v_cvt_pk_bf16_f32 v180, v58, v59
	v_cvt_pk_bf16_f32 v181, v60, v61
	global_store_dwordx2 v[218:219], v[180:181], off offset:32
	v_mul_f32_e32 v220, v59, v59
	v_mul_f32_e32 v221, v61, v61
	v_fmac_f32_e32 v220, v58, v58
	v_fmac_f32_e32 v221, v60, v60
	v_add_f32_e32 v58, v220, v221
	s_waitcnt vmcnt(31)
	v_lshlrev_b32_e32 v220, 16, v182
	v_and_b32_e32 v182, 0xffff0000, v182
	v_lshlrev_b32_e32 v221, 16, v183
	v_and_b32_e32 v183, 0xffff0000, v183
	v_add_f32_e32 v54, v54, v220
	v_add_f32_e32 v55, v55, v182
	v_add_f32_e32 v56, v56, v221
	v_add_f32_e32 v57, v57, v183
	v_cvt_pk_bf16_f32 v182, v54, v55
	v_cvt_pk_bf16_f32 v183, v56, v57
	global_store_dwordx2 v[218:219], v[182:183], off offset:256
	v_mul_f32_e32 v220, v55, v55
	v_mul_f32_e32 v221, v57, v57
	v_fmac_f32_e32 v220, v54, v54
	v_fmac_f32_e32 v221, v56, v56
	v_add_f32_e32 v54, v220, v221
	s_waitcnt vmcnt(31)
	v_lshlrev_b32_e32 v220, 16, v184
	v_and_b32_e32 v184, 0xffff0000, v184
	v_lshlrev_b32_e32 v221, 16, v185
	v_and_b32_e32 v185, 0xffff0000, v185
	v_add_f32_e32 v50, v50, v220
	v_add_f32_e32 v51, v51, v184
	v_add_f32_e32 v52, v52, v221
	v_add_f32_e32 v53, v53, v185
	v_cvt_pk_bf16_f32 v184, v50, v51
	v_cvt_pk_bf16_f32 v185, v52, v53
	global_store_dwordx2 v[218:219], v[184:185], off offset:288
	v_mul_f32_e32 v220, v51, v51
	v_mul_f32_e32 v221, v53, v53
	v_fmac_f32_e32 v220, v50, v50
	v_fmac_f32_e32 v221, v52, v52
	v_add_f32_e32 v50, v220, v221
	v_add_f32_e32 v58, v62, v58
	v_add_f32_e32 v54, v58, v54
	v_add_f32_e32 v50, v54, v50
	v_lshl_add_u64 v[218:219], v[218:219], 0, s[22:23]
	s_waitcnt vmcnt(31)
	v_lshlrev_b32_e32 v220, 16, v186
	v_and_b32_e32 v186, 0xffff0000, v186
	v_lshlrev_b32_e32 v221, 16, v187
	v_and_b32_e32 v187, 0xffff0000, v187
	v_add_f32_e32 v46, v46, v220
	v_add_f32_e32 v47, v47, v186
	v_add_f32_e32 v48, v48, v221
	v_add_f32_e32 v49, v49, v187
	v_cvt_pk_bf16_f32 v186, v46, v47
	v_cvt_pk_bf16_f32 v187, v48, v49
	global_store_dwordx2 v[218:219], v[186:187], off
	v_mul_f32_e32 v220, v47, v47
	v_mul_f32_e32 v221, v49, v49
	v_fmac_f32_e32 v220, v46, v46
	v_fmac_f32_e32 v221, v48, v48
	v_add_f32_e32 v46, v220, v221
	s_waitcnt vmcnt(31)
	v_lshlrev_b32_e32 v220, 16, v188
	v_and_b32_e32 v188, 0xffff0000, v188
	v_lshlrev_b32_e32 v221, 16, v189
	v_and_b32_e32 v189, 0xffff0000, v189
	v_add_f32_e32 v42, v42, v220
	v_add_f32_e32 v43, v43, v188
	v_add_f32_e32 v44, v44, v221
	v_add_f32_e32 v45, v45, v189
	v_cvt_pk_bf16_f32 v188, v42, v43
	v_cvt_pk_bf16_f32 v189, v44, v45
	global_store_dwordx2 v[218:219], v[188:189], off offset:32
	v_mul_f32_e32 v220, v43, v43
	v_mul_f32_e32 v221, v45, v45
	v_fmac_f32_e32 v220, v42, v42
	v_fmac_f32_e32 v221, v44, v44
	v_add_f32_e32 v42, v220, v221
	s_waitcnt vmcnt(31)
	v_lshlrev_b32_e32 v220, 16, v190
	v_and_b32_e32 v190, 0xffff0000, v190
	v_lshlrev_b32_e32 v221, 16, v191
	v_and_b32_e32 v191, 0xffff0000, v191
	v_add_f32_e32 v38, v38, v220
	v_add_f32_e32 v39, v39, v190
	v_add_f32_e32 v40, v40, v221
	v_add_f32_e32 v41, v41, v191
	v_cvt_pk_bf16_f32 v190, v38, v39
	v_cvt_pk_bf16_f32 v191, v40, v41
	global_store_dwordx2 v[218:219], v[190:191], off offset:256
	v_mul_f32_e32 v220, v39, v39
	v_mul_f32_e32 v221, v41, v41
	v_fmac_f32_e32 v220, v38, v38
	v_fmac_f32_e32 v221, v40, v40
	v_add_f32_e32 v38, v220, v221
	s_waitcnt vmcnt(31)
; __device__ __forceinline__ unsigned cvt_pk_bf16(float lo, float hi) { unsigned r; asm volatile("v_cvt_pk_bf16_f32 %0, %1, %2" : "=v"(r) : "v"(lo), "v"(hi)); return r; }
;     __device__ __forceinline__ void operator()(const f32x4 (&acc)[2][2][4][2], const Unit& u, int wr, int wc, int fr, int fq) const {
;     ...
;                     for (int n = 0; n < 2; ++n) { const u32x2_ bb = bv[bj][n]; f32x4 v = acc[ai][bj][m][n];
;                         v[0] += __uint_as_float(bb.x << 16); v[1] += __uint_as_float(bb.x & 0xffff0000u); v[2] += __uint_as_float(bb.y << 16); v[3] += __uint_as_float(bb.y & 0xffff0000u);
;                         u32x2_ w; w.x = cvt_pk_bf16(v[0], v[1]); w.y = cvt_pk_bf16(v[2], v[3]);
;                         *(u32x2_*)(xb + off + bj * HALF + n * 16) = w;
;                         q += (v[0] * v[0] + v[1] * v[1]) + (v[2] * v[2] + v[3] * v[3]); }
;                 q += __shfl_xor(q, 16); q += __shfl_xor(q, 32);
;                 if (fq == 0) red[wc * 256 + ai * HALF + wr * 64 + m * 16 + fr] = q; }
	v_lshlrev_b32_e32 v220, 16, v192
	v_and_b32_e32 v192, 0xffff0000, v192
	v_lshlrev_b32_e32 v221, 16, v193
	v_and_b32_e32 v193, 0xffff0000, v193
	v_add_f32_e32 v34, v34, v220
	v_add_f32_e32 v35, v35, v192
	v_add_f32_e32 v36, v36, v221
	v_add_f32_e32 v37, v37, v193
	v_cvt_pk_bf16_f32 v192, v34, v35
	v_cvt_pk_bf16_f32 v193, v36, v37
	global_store_dwordx2 v[218:219], v[192:193], off offset:288
	v_mul_f32_e32 v220, v35, v35
	v_mul_f32_e32 v221, v37, v37
	v_fmac_f32_e32 v220, v34, v34
	v_fmac_f32_e32 v221, v36, v36
	v_add_f32_e32 v34, v220, v221
	v_add_f32_e32 v42, v46, v42
	v_add_f32_e32 v38, v42, v38
	v_add_f32_e32 v34, v38, v34
	v_lshl_add_u64 v[218:219], v[218:219], 0, s[22:23]
	s_waitcnt vmcnt(31)
	v_lshlrev_b32_e32 v220, 16, v194
	v_and_b32_e32 v194, 0xffff0000, v194
	v_lshlrev_b32_e32 v221, 16, v195
	v_and_b32_e32 v195, 0xffff0000, v195
	v_add_f32_e32 v30, v30, v220
	v_add_f32_e32 v31, v31, v194
	v_add_f32_e32 v32, v32, v221
	v_add_f32_e32 v33, v33, v195
	v_cvt_pk_bf16_f32 v194, v30, v31
	v_cvt_pk_bf16_f32 v195, v32, v33
	global_store_dwordx2 v[218:219], v[194:195], off
	v_mul_f32_e32 v220, v31, v31
	v_mul_f32_e32 v221, v33, v33
	v_fmac_f32_e32 v220, v30, v30
	v_fmac_f32_e32 v221, v32, v32
	v_add_f32_e32 v30, v220, v221
	s_waitcnt vmcnt(31)
	v_lshlrev_b32_e32 v220, 16, v196
	v_and_b32_e32 v196, 0xffff0000, v196
	v_lshlrev_b32_e32 v221, 16, v197
	v_and_b32_e32 v197, 0xffff0000, v197
	v_add_f32_e32 v26, v26, v220
	v_add_f32_e32 v27, v27, v196
	v_add_f32_e32 v28, v28, v221
	v_add_f32_e32 v29, v29, v197
	v_cvt_pk_bf16_f32 v196, v26, v27
	v_cvt_pk_bf16_f32 v197, v28, v29
	global_store_dwordx2 v[218:219], v[196:197], off offset:32
	v_mul_f32_e32 v220, v27, v27
	v_mul_f32_e32 v221, v29, v29
	v_fmac_f32_e32 v220, v26, v26
	v_fmac_f32_e32 v221, v28, v28
	v_add_f32_e32 v26, v220, v221
	s_waitcnt vmcnt(31)
	v_lshlrev_b32_e32 v220, 16, v198
	v_and_b32_e32 v198, 0xffff0000, v198
	v_lshlrev_b32_e32 v221, 16, v199
	v_and_b32_e32 v199, 0xffff0000, v199
	v_add_f32_e32 v22, v22, v220
	v_add_f32_e32 v23, v23, v198
	v_add_f32_e32 v24, v24, v221
	v_add_f32_e32 v25, v25, v199
	v_cvt_pk_bf16_f32 v198, v22, v23
	v_cvt_pk_bf16_f32 v199, v24, v25
	global_store_dwordx2 v[218:219], v[198:199], off offset:256
	v_mul_f32_e32 v220, v23, v23
	v_mul_f32_e32 v221, v25, v25
	v_fmac_f32_e32 v220, v22, v22
	v_fmac_f32_e32 v221, v24, v24
	v_add_f32_e32 v22, v220, v221
	s_waitcnt vmcnt(31)
	v_lshlrev_b32_e32 v220, 16, v200
	v_and_b32_e32 v200, 0xffff0000, v200
	v_lshlrev_b32_e32 v221, 16, v201
	v_and_b32_e32 v201, 0xffff0000, v201
	v_add_f32_e32 v18, v18, v220
	v_add_f32_e32 v19, v19, v200
	v_add_f32_e32 v20, v20, v221
	v_add_f32_e32 v21, v21, v201
	v_cvt_pk_bf16_f32 v200, v18, v19
	v_cvt_pk_bf16_f32 v201, v20, v21
	global_store_dwordx2 v[218:219], v[200:201], off offset:288
	v_mul_f32_e32 v220, v19, v19
	v_mul_f32_e32 v221, v21, v21
	v_fmac_f32_e32 v220, v18, v18
	v_fmac_f32_e32 v221, v20, v20
	v_add_f32_e32 v18, v220, v221
	v_add_f32_e32 v26, v30, v26
	v_add_f32_e32 v22, v26, v22
	v_add_f32_e32 v18, v22, v18
	v_lshl_add_u64 v[218:219], v[218:219], 0, s[22:23]
	s_waitcnt vmcnt(31)
	v_lshlrev_b32_e32 v220, 16, v204
	v_and_b32_e32 v204, 0xffff0000, v204
	v_lshlrev_b32_e32 v221, 16, v205
	v_and_b32_e32 v205, 0xffff0000, v205
	v_add_f32_e32 v14, v14, v220
	v_add_f32_e32 v15, v15, v204
	v_add_f32_e32 v16, v16, v221
	v_add_f32_e32 v17, v17, v205
	v_cvt_pk_bf16_f32 v204, v14, v15
	v_cvt_pk_bf16_f32 v205, v16, v17
	global_store_dwordx2 v[218:219], v[204:205], off
	v_mul_f32_e32 v220, v15, v15
	v_mul_f32_e32 v221, v17, v17
	v_fmac_f32_e32 v220, v14, v14
	v_fmac_f32_e32 v221, v16, v16
	v_add_f32_e32 v14, v220, v221
	s_waitcnt vmcnt(31)
	v_lshlrev_b32_e32 v220, 16, v206
	v_and_b32_e32 v206, 0xffff0000, v206
	v_lshlrev_b32_e32 v221, 16, v207
	v_and_b32_e32 v207, 0xffff0000, v207
	v_add_f32_e32 v10, v10, v220
	v_add_f32_e32 v11, v11, v206
	v_add_f32_e32 v12, v12, v221
	v_add_f32_e32 v13, v13, v207
	v_cvt_pk_bf16_f32 v206, v10, v11
	v_cvt_pk_bf16_f32 v207, v12, v13
	global_store_dwordx2 v[218:219], v[206:207], off offset:32
	v_mul_f32_e32 v220, v11, v11
	v_mul_f32_e32 v221, v13, v13
	v_fmac_f32_e32 v220, v10, v10
	v_fmac_f32_e32 v221, v12, v12
	v_add_f32_e32 v10, v220, v221
	s_waitcnt vmcnt(31)
	v_lshlrev_b32_e32 v220, 16, v136
	v_and_b32_e32 v136, 0xffff0000, v136
	v_lshlrev_b32_e32 v221, 16, v137
	v_and_b32_e32 v137, 0xffff0000, v137
	v_add_f32_e32 v6, v6, v220
	v_add_f32_e32 v7, v7, v136
	v_add_f32_e32 v8, v8, v221
	v_add_f32_e32 v9, v9, v137
	v_cvt_pk_bf16_f32 v136, v6, v7
	v_cvt_pk_bf16_f32 v137, v8, v9
	global_store_dwordx2 v[218:219], v[136:137], off offset:256
	v_mul_f32_e32 v220, v7, v7
	v_mul_f32_e32 v221, v9, v9
	v_fmac_f32_e32 v220, v6, v6
	v_fmac_f32_e32 v221, v8, v8
	v_add_f32_e32 v6, v220, v221
	s_waitcnt vmcnt(31)
	v_lshlrev_b32_e32 v220, 16, v138
	v_and_b32_e32 v138, 0xffff0000, v138
	v_lshlrev_b32_e32 v221, 16, v139
	v_and_b32_e32 v139, 0xffff0000, v139
	v_add_f32_e32 v2, v2, v220
	v_add_f32_e32 v3, v3, v138
	v_add_f32_e32 v4, v4, v221
	v_add_f32_e32 v5, v5, v139
	v_cvt_pk_bf16_f32 v138, v2, v3
	v_cvt_pk_bf16_f32 v139, v4, v5
	global_store_dwordx2 v[218:219], v[138:139], off offset:288
	v_mul_f32_e32 v220, v3, v3
	v_mul_f32_e32 v221, v5, v5
	v_fmac_f32_e32 v220, v2, v2
	v_fmac_f32_e32 v221, v4, v4
	v_add_f32_e32 v2, v220, v221
	v_add_f32_e32 v10, v14, v10
	v_add_f32_e32 v6, v10, v6
	v_add_f32_e32 v2, v6, v2
	ds_bpermute_b32 v115, v222, v114
	ds_bpermute_b32 v99, v222, v98
	ds_bpermute_b32 v83, v222, v82
	ds_bpermute_b32 v67, v222, v66
	ds_bpermute_b32 v51, v222, v50
	ds_bpermute_b32 v35, v222, v34
	ds_bpermute_b32 v19, v222, v18
	ds_bpermute_b32 v3, v222, v2
	s_waitcnt lgkmcnt(7)
	v_add_f32_e32 v114, v114, v115
	s_waitcnt lgkmcnt(6)
	v_add_f32_e32 v98, v98, v99
	s_waitcnt lgkmcnt(5)
	v_add_f32_e32 v82, v82, v83
	s_waitcnt lgkmcnt(4)
	v_add_f32_e32 v66, v66, v67
	s_waitcnt lgkmcnt(3)
	v_add_f32_e32 v50, v50, v51
	s_waitcnt lgkmcnt(2)
	v_add_f32_e32 v34, v34, v35
	s_waitcnt lgkmcnt(1)
	v_add_f32_e32 v18, v18, v19
	s_waitcnt lgkmcnt(0)
	v_add_f32_e32 v2, v2, v3
	ds_bpermute_b32 v115, v223, v114
	ds_bpermute_b32 v99, v223, v98
	ds_bpermute_b32 v83, v223, v82
	ds_bpermute_b32 v67, v223, v66
	ds_bpermute_b32 v51, v223, v50
	ds_bpermute_b32 v35, v223, v34
	ds_bpermute_b32 v19, v223, v18
	ds_bpermute_b32 v3, v223, v2
	s_and_saveexec_b64 s[22:23], s[40:41]
	s_cbranch_execz .Lepires_skip_0
	s_waitcnt lgkmcnt(7)
	v_add_f32_e32 v114, v114, v115
	s_waitcnt lgkmcnt(6)
	v_add_f32_e32 v98, v98, v99
	s_waitcnt lgkmcnt(5)
	v_add_f32_e32 v82, v82, v83
	s_waitcnt lgkmcnt(4)
	v_add_f32_e32 v66, v66, v67
	s_waitcnt lgkmcnt(3)
	v_add_f32_e32 v50, v50, v51
	s_waitcnt lgkmcnt(2)
	v_add_f32_e32 v34, v34, v35
	s_waitcnt lgkmcnt(1)
	v_add_f32_e32 v18, v18, v19
	s_waitcnt lgkmcnt(0)
	v_add_f32_e32 v2, v2, v3
	ds_write_b32 v143, v114
	ds_write_b32 v143, v98 offset:64
	ds_write_b32 v143, v82 offset:128
	ds_write_b32 v143, v66 offset:192
	ds_write_b32 v143, v50 offset:512
	ds_write_b32 v143, v34 offset:576
	ds_write_b32 v143, v18 offset:640
	ds_write_b32 v143, v2 offset:704
